# v27 with the scan loader main loop unrolled by 2 with swapped chunk-data register sets: the 20 register copies per iteration are gone
# speedup vs baseline: 1.0020x; 1.0020x over previous
.Lub_206:
	v_add_u32_e32 v42, s20, v138
	v_cmp_lt_i32_e32 vcc, 0, v42
	v_lshl_add_u64 v[40:41], v[152:153], 0, s[20:21]
	v_lshl_add_u64 v[44:45], s[14:15], 0, v[154:155]
	v_cndmask_b32_e64 v42, 0, 1, vcc
	v_sub_co_u32_e32 v40, vcc, v40, v42
	v_lshl_add_u64 v[162:163], s[14:15], 0, v[150:151]
	s_nop 0
	v_subbrev_co_u32_e32 v43, vcc, 0, v41, vcc
	v_mad_u64_u32 v[40:41], s[22:23], v40, s75, v[146:147]
	v_mov_b32_e32 v42, v41
	v_mad_u64_u32 v[42:43], s[22:23], v43, s75, v[42:43]
	s_mov_b32 s22, 0x287d8000
	s_nop 0
	v_add_co_u32_e32 v46, vcc, s22, v44
	s_mov_b32 s22, 0x287d9000
	s_nop 0
	v_addc_co_u32_e32 v47, vcc, 0, v45, vcc
	v_add_co_u32_e32 v44, vcc, s22, v44
	v_mov_b32_e32 v41, v42
	s_nop 0
	v_addc_co_u32_e32 v45, vcc, 0, v45, vcc
	global_load_dwordx4 v[68:71], v[46:47], off offset:2048
	global_load_dwordx4 v[64:67], v[44:45], off
	v_add_co_u32_e32 v46, vcc, s74, v40
	s_nop 1
	v_addc_co_u32_e32 v47, vcc, 0, v42, vcc
	v_add_co_u32_e32 v42, vcc, 0x31730000, v162
	global_load_dwordx4 v[100:103], v[44:45], off offset:2048
	global_load_dwordx4 v[56:59], v[46:47], off
	v_addc_co_u32_e32 v43, vcc, 0, v163, vcc
	global_load_dwordx4 v[104:107], v[46:47], off offset:2048
	s_nop 0
	global_load_dwordx4 v[44:47], v[42:43], off
	v_add_co_u32_e32 v42, vcc, 0x33730000, v162
	s_waitcnt vmcnt(0)
	v_mov_b64_e32 v[90:91], v[46:47]
	v_addc_co_u32_e32 v43, vcc, 0, v163, vcc
	global_load_dwordx4 v[60:63], v[40:41], off offset:2048
	s_nop 0
	global_load_dwordx4 v[40:43], v[42:43], off
	v_mov_b64_e32 v[94:95], v[46:47]
	s_and_b64 vcc, exec, s[44:45]
	v_mov_b64_e32 v[88:89], v[44:45]
	v_mov_b64_e32 v[92:93], v[44:45]
	s_cbranch_vccnz .Lub_208
	v_add_co_u32_e32 v88, vcc, 0x37730000, v162
	s_nop 1
	v_addc_co_u32_e32 v89, vcc, 0, v163, vcc
	v_add_co_u32_e32 v92, vcc, 0x26730000, v162
	s_nop 1
	v_addc_co_u32_e32 v93, vcc, 0, v163, vcc
	global_load_dwordx4 v[88:91], v[88:89], off
	s_nop 0
	global_load_dwordx4 v[92:95], v[92:93], off

.Lcib_a_done:
	v_lshlrev_b32_e32 v156, 16, v116
	v_and_b32_e32 v116, 0xffff0000, v116
	v_lshlrev_b32_e32 v178, 16, v117
	v_and_b32_e32 v117, 0xffff0000, v117
	v_lshlrev_b32_e32 v179, 16, v118
	v_and_b32_e32 v118, 0xffff0000, v118
	v_lshlrev_b32_e32 v180, 16, v119
	v_and_b32_e32 v119, 0xffff0000, v119
	v_cmp_eq_u32_e64 s[48:49], s20, v136
	v_lshlrev_b32_e32 v162, 16, v112
	v_and_b32_e32 v163, 0xffff0000, v112
	v_lshlrev_b32_e32 v176, 16, v113
	v_and_b32_e32 v177, 0xffff0000, v113
	v_lshlrev_b32_e32 v112, 16, v114
	v_and_b32_e32 v113, 0xffff0000, v114
	v_lshlrev_b32_e32 v114, 16, v115
	v_and_b32_e32 v115, 0xffff0000, v115
	v_cndmask_b32_e64 v181, v119, 0, s[48:49]
	v_cndmask_b32_e64 v182, v179, 0, s[48:49]
	v_cndmask_b32_e64 v179, v118, 0, s[48:49]
	v_cndmask_b32_e64 v118, v178, 0, s[48:49]
	v_cndmask_b32_e64 v119, v117, 0, s[48:49]
	v_sub_f32_e32 v117, v116, v163
	v_sub_f32_e32 v116, v156, v162
	v_sub_f32_e32 v119, v119, v177
	v_sub_f32_e32 v118, v118, v176
	v_sub_f32_e32 v179, v179, v113
	v_sub_f32_e32 v178, v182, v112
	v_sub_f32_e32 v181, v181, v115
	v_sub_f32_e32 v180, v180, v114
	v_pk_fma_f32 v[114:115], v[38:39], v[180:181], v[114:115]
	v_pk_fma_f32 v[112:113], v[36:37], v[178:179], v[112:113]
	v_pk_fma_f32 v[118:119], v[34:35], v[118:119], v[176:177]
	s_and_b64 vcc, exec, s[44:45]
	v_pk_fma_f32 v[116:117], v[32:33], v[116:117], v[162:163]
	s_cbranch_vccnz .Lub_210
	v_lshlrev_b32_e32 v156, 16, v108
	v_and_b32_e32 v108, 0xffff0000, v108
	v_lshlrev_b32_e32 v162, 16, v109
	v_and_b32_e32 v163, 0xffff0000, v109
	v_lshlrev_b32_e32 v176, 16, v110
	v_and_b32_e32 v177, 0xffff0000, v110
	v_lshlrev_b32_e32 v178, 16, v111
	v_and_b32_e32 v179, 0xffff0000, v111
	v_sub_f32_e32 v109, v108, v117
	v_sub_f32_e32 v108, v156, v116
	v_sub_f32_e32 v111, v163, v119
	v_sub_f32_e32 v110, v162, v118
	v_sub_f32_e32 v163, v177, v113
	v_sub_f32_e32 v162, v176, v112
	v_sub_f32_e32 v177, v179, v115
	v_sub_f32_e32 v176, v178, v114
	v_lshlrev_b32_e32 v178, 16, v96
	v_and_b32_e32 v179, 0xffff0000, v96
	v_lshlrev_b32_e32 v96, 16, v97
	v_and_b32_e32 v97, 0xffff0000, v97
	v_lshlrev_b32_e32 v180, 16, v98
	v_and_b32_e32 v181, 0xffff0000, v98
	v_lshlrev_b32_e32 v98, 16, v99
	v_and_b32_e32 v99, 0xffff0000, v99
	v_pk_fma_f32 v[114:115], v[176:177], v[98:99], v[114:115]
	v_pk_fma_f32 v[112:113], v[162:163], v[180:181], v[112:113]
	v_pk_fma_f32 v[118:119], v[110:111], v[96:97], v[118:119]
	v_pk_fma_f32 v[116:117], v[108:109], v[178:179], v[116:117]
.Lub_210:
	v_lshlrev_b32_e32 v163, 16, v86
	v_and_b32_e32 v86, 0xffff0000, v86
	v_lshlrev_b32_e32 v176, 16, v87
	v_and_b32_e32 v87, 0xffff0000, v87
	v_lshlrev_b32_e32 v177, 16, v72
	v_and_b32_e32 v72, 0xffff0000, v72
	v_lshlrev_b32_e32 v178, 16, v73
	v_and_b32_e32 v73, 0xffff0000, v73
	v_lshlrev_b32_e32 v179, 16, v74
	v_and_b32_e32 v74, 0xffff0000, v74
	v_lshlrev_b32_e32 v180, 16, v75
	v_and_b32_e32 v75, 0xffff0000, v75
	v_lshlrev_b32_e32 v98, 16, v82
	v_and_b32_e32 v99, 0xffff0000, v82
	v_lshlrev_b32_e32 v82, 16, v83
	v_and_b32_e32 v83, 0xffff0000, v83
	v_cndmask_b32_e64 v181, v73, 0, s[48:49]
	v_cndmask_b32_e64 v182, v75, 0, s[48:49]
	v_cndmask_b32_e64 v183, v72, 0, s[48:49]
	v_cndmask_b32_e64 v184, v74, 0, s[48:49]
	v_cndmask_b32_e64 v74, v176, 0, s[48:49]
	v_cndmask_b32_e64 v75, v87, 0, s[48:49]
	v_cndmask_b32_e64 v72, v163, 0, s[48:49]
	v_cndmask_b32_e64 v73, v86, 0, s[48:49]
	v_lshlrev_b32_e32 v108, 16, v76
	v_and_b32_e32 v109, 0xffff0000, v76
	v_lshlrev_b32_e32 v110, 16, v78
	v_and_b32_e32 v111, 0xffff0000, v78
	v_sub_f32_e32 v73, v73, v99
	v_sub_f32_e32 v72, v72, v98
	v_sub_f32_e32 v75, v75, v83
	v_sub_f32_e32 v74, v74, v82
	v_lshlrev_b32_e32 v76, 16, v77
	v_and_b32_e32 v77, 0xffff0000, v77
	v_lshlrev_b32_e32 v78, 16, v79
	v_and_b32_e32 v79, 0xffff0000, v79
	v_lshlrev_b32_e32 v162, 16, v85
	v_pk_fma_f32 v[74:75], v[30:31], v[74:75], v[82:83]
	v_pk_fma_f32 v[72:73], v[28:29], v[72:73], v[98:99]
	v_sub_f32_e32 v83, v184, v111
	v_sub_f32_e32 v82, v179, v110
	v_sub_f32_e32 v99, v183, v109
	v_sub_f32_e32 v98, v177, v108
	v_cndmask_b32_e64 v86, v162, 0, s[48:49]
	v_sub_f32_e32 v163, v182, v79
	v_sub_f32_e32 v162, v180, v78
	v_sub_f32_e32 v177, v181, v77
	v_sub_f32_e32 v176, v178, v76
	v_pk_fma_f32 v[108:109], v[24:25], v[98:99], v[108:109]
	v_pk_fma_f32 v[98:99], v[20:21], v[82:83], v[110:111]
	v_pk_fma_f32 v[176:177], v[26:27], v[176:177], v[76:77]
	v_pk_fma_f32 v[162:163], v[22:23], v[162:163], v[78:79]
	v_pk_mul_f32 v[82:83], v[16:17], v[98:99]
	v_pk_mul_f32 v[110:111], v[12:13], v[108:109]
	v_pk_mul_f32 v[178:179], v[18:19], v[162:163]
	v_pk_mul_f32 v[180:181], v[14:15], v[176:177]
	v_pk_mul_f32 v[182:183], v[110:111], v[110:111]
	v_pk_mul_f32 v[184:185], v[82:83], v[82:83]
	v_pk_mul_f32 v[76:77], v[180:181], v[180:181]
	v_pk_mul_f32 v[78:79], v[178:179], v[178:179]
	v_mov_b32_e32 v186, v182
	v_mov_b32_e32 v187, v184
	v_mov_b32_e32 v184, v183
	v_pk_add_f32 v[182:183], v[186:187], v[184:185]
	v_mov_b32_e32 v184, v76
	v_mov_b32_e32 v185, v78
	v_mov_b32_e32 v78, v77
	v_pk_add_f32 v[76:77], v[184:185], v[78:79]
	v_and_b32_e32 v85, 0xffff0000, v85
	v_pk_add_f32 v[76:77], v[182:183], v[76:77]
	v_lshlrev_b32_e32 v96, 16, v80
	v_add_f32_e32 v76, v76, v77
	ds_bpermute_b32 v77, v165, v76
	v_and_b32_e32 v97, 0xffff0000, v80
	v_lshlrev_b32_e32 v80, 16, v81
	v_and_b32_e32 v81, 0xffff0000, v81
	v_lshlrev_b32_e32 v156, 16, v84
	v_and_b32_e32 v84, 0xffff0000, v84
	v_cndmask_b32_e64 v87, v85, 0, s[48:49]
	v_sub_f32_e32 v87, v87, v81
	v_sub_f32_e32 v86, v86, v80
	v_sub_f32_e32 v85, v84, v97
	v_sub_f32_e32 v84, v156, v96
	v_pk_fma_f32 v[86:87], v[10:11], v[86:87], v[80:81]
	v_lshlrev_b32_e32 v81, 16, v52
	v_and_b32_e32 v156, 0xffff0000, v52
	s_waitcnt lgkmcnt(0)
	v_add_f32_e32 v52, v76, v77
	ds_bpermute_b32 v76, v166, v52
	v_lshlrev_b32_e32 v192, 16, v53
	v_and_b32_e32 v193, 0xffff0000, v53
	v_lshlrev_b32_e32 v194, 16, v54
	v_and_b32_e32 v195, 0xffff0000, v54
	s_waitcnt lgkmcnt(0)
	v_add_f32_e32 v52, v52, v76
	ds_bpermute_b32 v53, v167, v52
	v_lshlrev_b32_e32 v202, 16, v55
	v_and_b32_e32 v203, 0xffff0000, v55
	v_lshlrev_b32_e32 v54, 16, v48
	v_and_b32_e32 v55, 0xffff0000, v48
	s_waitcnt lgkmcnt(0)
	v_add_f32_e32 v48, v52, v53
	v_mul_f32_e32 v52, 0x4f800000, v48
	v_cmp_gt_f32_e32 vcc, s76, v48
	v_lshlrev_b32_e32 v184, 16, v50
	v_and_b32_e32 v185, 0xffff0000, v50
	v_cndmask_b32_e32 v52, v48, v52, vcc
	v_sqrt_f32_e32 v53, v52
	v_lshlrev_b32_e32 v182, 16, v51
	v_and_b32_e32 v183, 0xffff0000, v51
	v_lshlrev_b32_e32 v48, 16, v49
	v_add_u32_e32 v76, -1, v53
	v_fma_f32 v77, -v76, v53, v52
	v_cmp_ge_f32_e64 s[48:49], 0, v77
	v_add_u32_e32 v77, 1, v53
	v_and_b32_e32 v49, 0xffff0000, v49
	v_cndmask_b32_e64 v76, v53, v76, s[48:49]
	v_fma_f32 v53, -v77, v53, v52
	v_cmp_lt_f32_e64 s[48:49], 0, v53
	s_bitcmp1_b32 s19, 0
	v_pk_add_f32 v[78:79], v[54:55], -1.0 op_sel_hi:[1,0]
	v_cndmask_b32_e64 v53, v76, v77, s[48:49]
	v_mul_f32_e32 v76, 0x37800000, v53
	v_cndmask_b32_e32 v53, v53, v76, vcc
	v_cmp_class_f32_e32 vcc, v52, v196
	v_pk_fma_f32 v[84:85], v[8:9], v[84:85], v[96:97]
	v_pk_fma_f32 v[96:97], v[4:5], v[78:79], 1.0 op_sel_hi:[1,1,0]
	v_cndmask_b32_e32 v52, v53, v52, vcc
	v_max_f32_e32 v52, 0x2b8cbccc, v52
	v_div_scale_f32 v53, s[22:23], v52, v52, 1.0
	v_rcp_f32_e32 v76, v53
	s_cselect_b32 s22, 0xa800, 0
	v_mul_f32_e32 v78, 0x3fb8aa3b, v202
	v_mul_f32_e32 v79, 0x3fb8aa3b, v203
	v_fma_f32 v50, -v53, v76, 1.0
	v_fmac_f32_e32 v76, v50, v76
	v_div_scale_f32 v50, vcc, 1.0, v52, 1.0
	v_mul_f32_e32 v51, v50, v76
	v_fma_f32 v77, -v53, v51, v50
	v_fmac_f32_e32 v51, v77, v76
	v_fma_f32 v50, -v53, v51, v50
	v_div_fmas_f32 v50, v50, v76, v51
	v_div_fixup_f32 v80, v50, v52, 1.0
	v_pk_add_f32 v[50:51], v[182:183], -1.0 op_sel_hi:[1,0]
	v_pk_add_f32 v[52:53], v[184:185], -1.0 op_sel_hi:[1,0]
	v_pk_add_f32 v[76:77], v[48:49], -1.0 op_sel_hi:[1,0]
	v_pk_fma_f32 v[188:189], v[0:1], v[52:53], 1.0 op_sel_hi:[1,1,0]
	v_pk_fma_f32 v[186:187], v[6:7], v[76:77], 1.0 op_sel_hi:[1,1,0]
	v_pk_fma_f32 v[190:191], v[2:3], v[50:51], 1.0 op_sel_hi:[1,1,0]
	v_mul_f32_e32 v50, 0x3fb8aa3b, v81
	v_mul_f32_e32 v51, 0x3fb8aa3b, v156
	v_mul_f32_e32 v52, 0x3fb8aa3b, v192
	v_mul_f32_e32 v53, 0x3fb8aa3b, v193
	v_mul_f32_e32 v76, 0x3fb8aa3b, v194
	v_mul_f32_e32 v77, 0x3fb8aa3b, v195
	v_pk_mul_f32 v[194:195], v[180:181], v[80:81] op_sel_hi:[1,0]
	v_exp_f32_e32 v50, v50
	v_exp_f32_e32 v51, v51
	v_exp_f32_e32 v52, v52
	v_exp_f32_e32 v53, v53
	v_pk_mul_f32 v[192:193], v[110:111], v[80:81] op_sel_hi:[1,0]
	v_pk_mul_f32 v[180:181], v[82:83], v[80:81] op_sel_hi:[1,0]
	v_pk_mul_f32 v[202:203], v[178:179], v[80:81] op_sel_hi:[1,0]
	v_pk_mul_f32 v[80:81], v[188:189], v[98:99]
	v_pk_mul_f32 v[98:99], v[186:187], v[176:177]
	v_pk_mul_f32 v[186:187], v[194:195], v[48:49]
	v_add_u32_e32 v48, s22, v168
	v_exp_f32_e32 v76, v76
	v_exp_f32_e32 v77, v77
	v_exp_f32_e32 v78, v78
	v_exp_f32_e32 v79, v79
	v_add_u32_e32 v49, v48, v169
	v_pk_mul_f32 v[82:83], v[190:191], v[162:163]
	v_pk_mul_f32 v[96:97], v[96:97], v[108:109]
	v_xor_b32_e32 v111, 0x80000000, v203
	v_xor_b32_e32 v110, 0x80000000, v202
	v_xor_b32_e32 v109, 0x80000000, v181
	v_xor_b32_e32 v108, 0x80000000, v180
	v_xor_b32_e32 v179, 0x80000000, v195
	v_xor_b32_e32 v178, 0x80000000, v194
	v_xor_b32_e32 v177, 0x80000000, v193
	v_xor_b32_e32 v176, 0x80000000, v192
	v_pk_mul_f32 v[182:183], v[202:203], v[182:183]
	v_pk_mul_f32 v[180:181], v[180:181], v[184:185]
	v_pk_mul_f32 v[184:185], v[192:193], v[54:55]
	ds_write_b128 v49, v[84:87]
	ds_write_b128 v49, v[72:75] offset:16
	ds_write_b128 v49, v[50:53] offset:256
	ds_write_b128 v49, v[76:79] offset:272
	ds_write_b128 v49, v[96:99] offset:512
	ds_write_b128 v49, v[80:83] offset:528
	ds_write_b128 v49, v[176:179] offset:768
	ds_write_b128 v49, v[108:111] offset:784
	ds_write_b128 v49, v[184:187] offset:1024
	ds_write_b128 v49, v[180:183] offset:1040
	s_and_saveexec_b64 s[22:23], s[46:47]
	s_cbranch_execz .Lub_212
	v_add_u32_e32 v48, v48, v170
	ds_write_b128 v48, v[116:119] offset:1280
	ds_write_b128 v48, v[112:115] offset:1296
.Lub_212:
	s_or_b64 exec, exec, s[22:23]
	s_and_b32 s22, s24, 0x800
	s_addk_i32 s24, 0x800
	v_add_u32_e32 v48, s22, v171
	s_add_u32 s20, s20, 32
	ds_read_b64 v[48:49], v48
	s_addc_u32 s21, s21, 0
	s_mov_b64 s[22:23], 0x48000
	s_add_i32 s19, s19, 1
	s_waitcnt lgkmcnt(0)
	v_cvt_pk_bf16_f32 v50, v48, v49
	v_lshl_add_u64 v[48:49], s[14:15], 0, v[148:149]
	v_lshl_add_u64 v[148:149], v[148:149], 0, s[92:93]
	v_lshl_add_u64 v[150:151], v[150:151], 0, s[92:93]
	v_lshl_add_u64 v[154:155], v[154:155], 0, s[22:23]
	s_cmp_eq_u32 s53, 1
	s_cbranch_scc0 .Lcib_b_done
	s_waitcnt vmcnt(0)
	s_cmp_eq_u32 s61, 2
	s_cbranch_scc1 .Lcib_b_flat
	s_cmp_eq_u32 s61, 0
	s_cbranch_scc1 .Lcib_b_nogs
	v_pk_mul_f32 v[232:233], v[232:233], v[248:249] op_sel_hi:[1,0]
	v_pk_mul_f32 v[234:235], v[234:235], v[248:249] op_sel_hi:[1,0]
	v_pk_mul_f32 v[236:237], v[236:237], v[248:249] op_sel:[0,1] op_sel_hi:[1,1]
	v_pk_mul_f32 v[238:239], v[238:239], v[248:249] op_sel:[0,1] op_sel_hi:[1,1]
	v_pk_mul_f32 v[240:241], v[240:241], v[250:251] op_sel_hi:[1,0]
	v_pk_mul_f32 v[242:243], v[242:243], v[250:251] op_sel_hi:[1,0]
	v_pk_mul_f32 v[244:245], v[244:245], v[250:251] op_sel:[0,1] op_sel_hi:[1,1]
	v_pk_mul_f32 v[246:247], v[246:247], v[250:251] op_sel:[0,1] op_sel_hi:[1,1]

.Lcib_b_done:
	s_cmpk_eq_i32 s20, 0xfa0
	global_store_dword v[48:49], v50, off
	s_barrier
	s_cbranch_scc1 .Lub_exit
	s_waitcnt vmcnt(1)
	s_branch .LBB0_206
